# FFN-down steady-state loop copy: the 12 never-taken guard branches per iteration removed (guards are statically true for iterations 2..58)
# speedup vs baseline: 1.0119x; 1.0035x over previous
; #define G_LOAD(S, kt_) do { G_LD1(S##a0, S##b0, 0, kt_); G_LD1(S##a1, S##b1, 1, kt_); G_LD1(S##a2, S##b2, 2, kt_); G_LD1(S##a3, S##b3, 3, kt_); } while (0)
; #define G_STORE(S, buf_) do { G_ST1(S##a0, S##b0, 0, buf_); G_ST1(S##a1, S##b1, 1, buf_); G_ST1(S##a2, S##b2, 2, buf_); G_ST1(S##a3, S##b3, 3, buf_); } while (0)
; template <class AL, class BL>
; DI void gemm_core(AL al, BL bl, int m0, int n0, int K, char* smem, f32x16 (&acc)[2][2]) {
;     ...
;   G_LOAD(x, 0);
;   G_STORE(x, 0);
;   G_LOAD(x, 1);
;   G_LOAD(y, (nk > 2) ? 2 : 1);
;   __syncthreads();
;   for (int kt = 0; kt < nk; kt += 2) {
;     G_TILE(0, x, true, (kt + 3 < nk), kt + 3);
;     __syncthreads();
;     G_TILE(1, y, (kt + 2 < nk), (kt + 4 < nk), kt + 4);
;     __syncthreads();
;   }
.Lfd0_hdr:
	ds_read_b128 v[132:135], v160
	ds_read_b128 v[144:147], v159 offset:36864
	ds_read_b128 v[136:139], v160 offset:32
	ds_read_b128 v[140:143], v159 offset:36896
	ds_read_b128 v[148:151], v159 offset:41472
	ds_read_b128 v[128:131], v159 offset:41504
	s_cmp_lt_u32 s1, 61
	s_waitcnt lgkmcnt(4)
	v_mfma_f32_32x32x16_bf16 v[48:63], v[132:135], v[144:147], v[48:63]
	s_cselect_b64 s[2:3], -1, 0
	s_cmp_gt_u32 s1, 60
	v_lshl_add_u64 v[188:189], v[164:165], 0, v[156:157]
	v_lshl_add_u64 v[184:185], v[162:163], 0, v[156:157]
	s_waitcnt lgkmcnt(1)
	v_mfma_f32_32x32x16_bf16 v[32:47], v[132:135], v[148:151], v[32:47]
	ds_read_b128 v[152:155], v160 offset:4608
	ds_read_b128 v[132:135], v160 offset:4640
	s_waitcnt vmcnt(15)
	ds_write_b128 v158, v[64:67] offset:18432
	s_waitcnt vmcnt(14)
	ds_write_b128 v158, v[72:75] offset:55296
	s_waitcnt lgkmcnt(3)
	v_mfma_f32_32x32x16_bf16 v[16:31], v[152:155], v[144:147], v[16:31]
	v_mfma_f32_32x32x16_bf16 v[0:15], v[152:155], v[148:151], v[0:15]
	v_add_co_u32_e32 v64, vcc, 0x4c00000, v188
	s_nop 1
	v_addc_co_u32_e32 v65, vcc, 0, v189, vcc
	v_add_co_u32_e32 v72, vcc, 0xe400000, v184
	global_load_dwordx4 v[64:67], v[64:65], off offset:384
	s_nop 0
	v_addc_co_u32_e32 v73, vcc, 0, v185, vcc
	global_load_dwordx4 v[72:75], v[72:73], off offset:384
.Lfd0_1046:
	v_mfma_f32_32x32x16_bf16 v[48:63], v[136:139], v[140:143], v[48:63]
	s_andn2_b64 vcc, exec, s[2:3]
	v_lshl_add_u64 v[186:187], v[166:167], 0, v[156:157]
	v_lshl_add_u64 v[180:181], v[168:169], 0, v[156:157]
	v_mfma_f32_32x32x16_bf16 v[32:47], v[136:139], v[128:131], v[32:47]
	ds_read_b128 v[152:155], v160 offset:64
	ds_read_b128 v[136:139], v160 offset:4672
	ds_read_b128 v[148:151], v159 offset:36928
	ds_read_b128 v[144:147], v159 offset:41536
	s_waitcnt vmcnt(15)
	ds_write_b128 v158, v[84:87] offset:23040
	s_waitcnt vmcnt(14)
	ds_write_b128 v158, v[80:83] offset:59904
	s_waitcnt lgkmcnt(8)
	v_mfma_f32_32x32x16_bf16 v[16:31], v[132:135], v[140:143], v[16:31]
	v_cndmask_b32_e64 v140, 0, 1, s[2:3]
	v_cmp_ne_u32_e64 s[12:13], 1, v140
	v_mfma_f32_32x32x16_bf16 v[0:15], v[132:135], v[128:131], v[0:15]
	v_add_co_u32_e32 v80, vcc, 0x4c00000, v186
	s_nop 1
	v_addc_co_u32_e32 v81, vcc, 0, v187, vcc
	global_load_dwordx4 v[84:87], v[80:81], off offset:384
	v_add_co_u32_e32 v80, vcc, 0xe400000, v180
	s_nop 1
	v_addc_co_u32_e32 v81, vcc, 0, v181, vcc
	global_load_dwordx4 v[80:83], v[80:81], off offset:384
.Lfd0_1048:
	s_waitcnt lgkmcnt(3)
	v_mfma_f32_32x32x16_bf16 v[48:63], v[152:155], v[148:151], v[48:63]
	ds_read_b128 v[140:143], v160 offset:96
	ds_read_b128 v[128:131], v160 offset:4704
	s_and_b64 vcc, exec, s[12:13]
	v_lshl_add_u64 v[182:183], v[170:171], 0, v[156:157]
	s_waitcnt lgkmcnt(4)
	v_mfma_f32_32x32x16_bf16 v[32:47], v[152:155], v[144:147], v[32:47]
	v_lshl_add_u64 v[154:155], v[172:173], 0, v[156:157]
	v_mfma_f32_32x32x16_bf16 v[16:31], v[136:139], v[148:151], v[16:31]
	ds_read_b128 v[148:151], v159 offset:36960
	ds_read_b128 v[132:135], v159 offset:41568
	s_waitcnt vmcnt(15)
	ds_write_b128 v158, v[88:91] offset:27648
	s_waitcnt vmcnt(14)
	ds_write_b128 v158, v[96:99] offset:64512
	v_mfma_f32_32x32x16_bf16 v[0:15], v[136:139], v[144:147], v[0:15]
	v_add_co_u32_e32 v88, vcc, 0x4c00000, v182
	s_nop 1
	v_addc_co_u32_e32 v89, vcc, 0, v183, vcc
	v_add_co_u32_e32 v96, vcc, 0xe400000, v154
	global_load_dwordx4 v[88:91], v[88:89], off offset:384
	s_nop 0
	v_addc_co_u32_e32 v97, vcc, 0, v155, vcc
	global_load_dwordx4 v[96:99], v[96:97], off offset:384
.Lfd0_1050:
	s_waitcnt lgkmcnt(3)
	v_mfma_f32_32x32x16_bf16 v[48:63], v[140:143], v[148:151], v[48:63]
	s_and_b64 vcc, exec, s[12:13]
	v_lshl_add_u64 v[178:179], v[174:175], 0, v[156:157]
	v_lshl_add_u64 v[152:153], v[176:177], 0, v[156:157]
	s_waitcnt vmcnt(15)
	ds_write_b128 v158, v[100:103] offset:32256
	s_waitcnt vmcnt(14)
	ds_write_b128 v161, v[112:115] offset:32256
	s_waitcnt lgkmcnt(4)
	v_mfma_f32_32x32x16_bf16 v[32:47], v[140:143], v[132:135], v[32:47]
	v_mfma_f32_32x32x16_bf16 v[16:31], v[128:131], v[148:151], v[16:31]
	v_mfma_f32_32x32x16_bf16 v[0:15], v[128:131], v[132:135], v[0:15]
	v_add_co_u32_e32 v100, vcc, 0x4c00000, v178
	s_nop 1
	v_addc_co_u32_e32 v101, vcc, 0, v179, vcc
	v_add_co_u32_e32 v112, vcc, 0xe400000, v152
	global_load_dwordx4 v[100:103], v[100:101], off offset:384
	s_nop 0
	v_addc_co_u32_e32 v113, vcc, 0, v153, vcc
	global_load_dwordx4 v[112:115], v[112:113], off offset:384
; #define G_LOAD(S, kt_) do { G_LD1(S##a0, S##b0, 0, kt_); G_LD1(S##a1, S##b1, 1, kt_); G_LD1(S##a2, S##b2, 2, kt_); G_LD1(S##a3, S##b3, 3, kt_); } while (0)
; #define G_STORE(S, buf_) do { G_ST1(S##a0, S##b0, 0, buf_); G_ST1(S##a1, S##b1, 1, buf_); G_ST1(S##a2, S##b2, 2, buf_); G_ST1(S##a3, S##b3, 3, buf_); } while (0)
; template <class AL, class BL>
; DI void gemm_core(AL al, BL bl, int m0, int n0, int K, char* smem, f32x16 (&acc)[2][2]) {
;     ...
;   G_LOAD(x, 0);
;   G_STORE(x, 0);
;   G_LOAD(x, 1);
;   G_LOAD(y, (nk > 2) ? 2 : 1);
;   __syncthreads();
;   for (int kt = 0; kt < nk; kt += 2) {
;     G_TILE(0, x, true, (kt + 3 < nk), kt + 3);
;     __syncthreads();
;     G_TILE(1, y, (kt + 2 < nk), (kt + 4 < nk), kt + 4);
;     __syncthreads();
;   }
.Lfd0_1052:
	s_waitcnt lgkmcnt(0)
	s_barrier
	ds_read_b128 v[132:135], v160 offset:18432
	ds_read_b128 v[144:147], v159 offset:55296
	ds_read_b128 v[140:143], v160 offset:18464
	ds_read_b128 v[136:139], v159 offset:55328
	ds_read_b128 v[148:151], v159 offset:59904
	ds_read_b128 v[128:131], v159 offset:59936
	s_waitcnt lgkmcnt(4)
	v_mfma_f32_32x32x16_bf16 v[48:63], v[132:135], v[144:147], v[48:63]
	s_cmp_lt_u32 s1, 62
	s_cselect_b64 s[14:15], -1, 0
	s_cmp_gt_u32 s1, 61
	s_cselect_b64 s[2:3], -1, 0
	s_and_b64 vcc, exec, s[2:3]
	s_waitcnt lgkmcnt(1)
	v_mfma_f32_32x32x16_bf16 v[32:47], v[132:135], v[148:151], v[32:47]
	ds_read_b128 v[190:193], v160 offset:23040
	ds_read_b128 v[132:135], v160 offset:23072
	s_waitcnt lgkmcnt(1)
	v_mfma_f32_32x32x16_bf16 v[16:31], v[190:193], v[144:147], v[16:31]
	v_mfma_f32_32x32x16_bf16 v[0:15], v[190:193], v[148:151], v[0:15]
	s_waitcnt vmcnt(15)
	ds_write_b128 v158, v[68:71]
	s_waitcnt vmcnt(14)
	ds_write_b128 v158, v[76:79] offset:36864
.Lfd0_1054:
	s_cmp_lt_u32 s1, 60
	s_cselect_b64 s[40:41], -1, 0
	s_cmp_gt_u32 s1, 59
	v_add_co_u32_e32 v68, vcc, 0x4c00000, v188
	s_nop 1
	v_addc_co_u32_e32 v69, vcc, 0, v189, vcc
	v_add_co_u32_e32 v76, vcc, 0xe400000, v184
	global_load_dwordx4 v[68:71], v[68:69], off offset:512
	s_nop 0
	v_addc_co_u32_e32 v77, vcc, 0, v185, vcc
	global_load_dwordx4 v[76:79], v[76:77], off offset:512
.Lfd0_1056:
	v_mfma_f32_32x32x16_bf16 v[48:63], v[140:143], v[136:139], v[48:63]
	v_cndmask_b32_e64 v184, 0, 1, s[14:15]
	v_cmp_ne_u32_e64 s[12:13], 1, v184
	s_andn2_b64 vcc, exec, s[14:15]
	v_mfma_f32_32x32x16_bf16 v[32:47], v[140:143], v[128:131], v[32:47]
	s_waitcnt lgkmcnt(0)
	v_mfma_f32_32x32x16_bf16 v[16:31], v[132:135], v[136:139], v[16:31]
	ds_read_b128 v[144:147], v160 offset:18496
	ds_read_b128 v[136:139], v160 offset:23104
	ds_read_b128 v[148:151], v159 offset:55360
	ds_read_b128 v[140:143], v159 offset:59968
	v_mfma_f32_32x32x16_bf16 v[0:15], v[132:135], v[128:131], v[0:15]
	s_waitcnt vmcnt(15)
	ds_write_b128 v158, v[104:107] offset:4608
	s_waitcnt vmcnt(14)
	ds_write_b128 v158, v[92:95] offset:41472
.Lfd0_1058:
	v_cndmask_b32_e64 v128, 0, 1, s[40:41]
	v_cmp_ne_u32_e64 s[14:15], 1, v128
	s_andn2_b64 vcc, exec, s[40:41]
	v_add_co_u32_e32 v92, vcc, 0x4c00000, v186
	s_nop 1
	v_addc_co_u32_e32 v93, vcc, 0, v187, vcc
	global_load_dwordx4 v[104:107], v[92:93], off offset:512
	v_add_co_u32_e32 v92, vcc, 0xe400000, v180
	s_nop 1
	v_addc_co_u32_e32 v93, vcc, 0, v181, vcc
	global_load_dwordx4 v[92:95], v[92:93], off offset:512
.Lfd0_1060:
	s_waitcnt lgkmcnt(1)
	v_mfma_f32_32x32x16_bf16 v[48:63], v[144:147], v[148:151], v[48:63]
	s_and_b64 vcc, exec, s[12:13]
	s_waitcnt lgkmcnt(0)
	v_mfma_f32_32x32x16_bf16 v[32:47], v[144:147], v[140:143], v[32:47]
	v_mfma_f32_32x32x16_bf16 v[16:31], v[136:139], v[148:151], v[16:31]
	ds_read_b128 v[144:147], v160 offset:18528
	ds_read_b128 v[128:131], v160 offset:23136
	ds_read_b128 v[148:151], v159 offset:55392
	ds_read_b128 v[132:135], v159 offset:60000
	v_mfma_f32_32x32x16_bf16 v[0:15], v[136:139], v[140:143], v[0:15]
	s_waitcnt vmcnt(15)
	ds_write_b128 v158, v[116:119] offset:9216
	s_waitcnt vmcnt(14)
	ds_write_b128 v158, v[108:111] offset:46080
.Lfd0_1062:
	s_and_b64 vcc, exec, s[14:15]
	v_add_co_u32_e32 v108, vcc, 0x4c00000, v182
	s_nop 1
	v_addc_co_u32_e32 v109, vcc, 0, v183, vcc
	global_load_dwordx4 v[116:119], v[108:109], off offset:512
	v_add_co_u32_e32 v108, vcc, 0xe400000, v154
	s_nop 1
	v_addc_co_u32_e32 v109, vcc, 0, v155, vcc
	global_load_dwordx4 v[108:111], v[108:109], off offset:512
.Lfd0_1064:
	s_waitcnt lgkmcnt(1)
	v_mfma_f32_32x32x16_bf16 v[48:63], v[144:147], v[148:151], v[48:63]
	s_and_b64 vcc, exec, s[12:13]
	s_waitcnt lgkmcnt(0)
	v_mfma_f32_32x32x16_bf16 v[32:47], v[144:147], v[132:135], v[32:47]
	v_mfma_f32_32x32x16_bf16 v[16:31], v[128:131], v[148:151], v[16:31]
	v_mfma_f32_32x32x16_bf16 v[0:15], v[128:131], v[132:135], v[0:15]
	s_waitcnt vmcnt(15)
	ds_write_b128 v158, v[124:127] offset:13824
	s_waitcnt vmcnt(14)
	ds_write_b128 v158, v[120:123] offset:50688
.Lfd0_1066:
	s_and_b64 vcc, exec, s[14:15]
	v_add_co_u32_e32 v120, vcc, 0x4c00000, v178
	s_nop 1
	v_addc_co_u32_e32 v121, vcc, 0, v179, vcc
	global_load_dwordx4 v[124:127], v[120:121], off offset:512
	v_add_co_u32_e32 v120, vcc, 0xe400000, v152
	s_nop 1
	v_addc_co_u32_e32 v121, vcc, 0, v153, vcc
	global_load_dwordx4 v[120:123], v[120:121], off offset:512
	s_branch .Lfd0_latch

; #define G_LOAD(S, kt_) do { G_LD1(S##a0, S##b0, 0, kt_); G_LD1(S##a1, S##b1, 1, kt_); G_LD1(S##a2, S##b2, 2, kt_); G_LD1(S##a3, S##b3, 3, kt_); } while (0)
; #define G_STORE(S, buf_) do { G_ST1(S##a0, S##b0, 0, buf_); G_ST1(S##a1, S##b1, 1, buf_); G_ST1(S##a2, S##b2, 2, buf_); G_ST1(S##a3, S##b3, 3, buf_); } while (0)
; template <class AL, class BL>
; DI void gemm_core(AL al, BL bl, int m0, int n0, int K, char* smem, f32x16 (&acc)[2][2]) {
;     ...
;   G_LOAD(x, 0);
;   G_STORE(x, 0);
;   G_LOAD(x, 1);
;   G_LOAD(y, (nk > 2) ? 2 : 1);
;   __syncthreads();
;   for (int kt = 0; kt < nk; kt += 2) {
;     G_TILE(0, x, true, (kt + 3 < nk), kt + 3);
;     __syncthreads();
;     G_TILE(1, y, (kt + 2 < nk), (kt + 4 < nk), kt + 4);
;     __syncthreads();
;   }
.Lfd1_hdr:
	ds_read_b128 v[132:135], v160
	ds_read_b128 v[144:147], v159 offset:36864
	ds_read_b128 v[136:139], v160 offset:32
	ds_read_b128 v[140:143], v159 offset:36896
	ds_read_b128 v[148:151], v159 offset:41472
	ds_read_b128 v[128:131], v159 offset:41504
	s_cmp_lt_u32 s1, 61
	s_waitcnt lgkmcnt(4)
	v_mfma_f32_32x32x16_bf16 v[48:63], v[132:135], v[144:147], v[48:63]
	s_cselect_b64 s[2:3], -1, 0
	s_cmp_gt_u32 s1, 60
	v_lshl_add_u64 v[188:189], v[164:165], 0, v[156:157]
	v_lshl_add_u64 v[184:185], v[162:163], 0, v[156:157]
	s_waitcnt lgkmcnt(1)
	v_mfma_f32_32x32x16_bf16 v[32:47], v[132:135], v[148:151], v[32:47]
	ds_read_b128 v[152:155], v160 offset:4608
	ds_read_b128 v[132:135], v160 offset:4640
	s_waitcnt vmcnt(15)
	ds_write_b128 v158, v[64:67] offset:18432
	s_waitcnt vmcnt(14)
	ds_write_b128 v158, v[72:75] offset:55296
	s_waitcnt lgkmcnt(3)
	v_mfma_f32_32x32x16_bf16 v[16:31], v[152:155], v[144:147], v[16:31]
	v_mfma_f32_32x32x16_bf16 v[0:15], v[152:155], v[148:151], v[0:15]
	v_add_co_u32_e32 v64, vcc, 0x8000000, v188
	s_nop 1
	v_addc_co_u32_e32 v65, vcc, 0, v189, vcc
	v_add_co_u32_e32 v72, vcc, 0x7800000, v184
	global_load_dwordx4 v[64:67], v[64:65], off offset:384
	s_nop 0
	v_addc_co_u32_e32 v73, vcc, 0, v185, vcc
	global_load_dwordx4 v[72:75], v[72:73], off offset:384
.Lfd1_1742:
	v_mfma_f32_32x32x16_bf16 v[48:63], v[136:139], v[140:143], v[48:63]
	s_andn2_b64 vcc, exec, s[2:3]
	v_lshl_add_u64 v[186:187], v[166:167], 0, v[156:157]
	v_lshl_add_u64 v[180:181], v[168:169], 0, v[156:157]
	v_mfma_f32_32x32x16_bf16 v[32:47], v[136:139], v[128:131], v[32:47]
	ds_read_b128 v[152:155], v160 offset:64
	ds_read_b128 v[136:139], v160 offset:4672
	ds_read_b128 v[148:151], v159 offset:36928
	ds_read_b128 v[144:147], v159 offset:41536
	s_waitcnt vmcnt(15)
	ds_write_b128 v158, v[96:99] offset:23040
	s_waitcnt vmcnt(14)
	ds_write_b128 v158, v[80:83] offset:59904
	s_waitcnt lgkmcnt(8)
	v_mfma_f32_32x32x16_bf16 v[16:31], v[132:135], v[140:143], v[16:31]
	v_cndmask_b32_e64 v140, 0, 1, s[2:3]
	v_cmp_ne_u32_e64 s[6:7], 1, v140
	v_mfma_f32_32x32x16_bf16 v[0:15], v[132:135], v[128:131], v[0:15]
	v_add_co_u32_e32 v80, vcc, 0x8000000, v186
	s_nop 1
	v_addc_co_u32_e32 v81, vcc, 0, v187, vcc
	global_load_dwordx4 v[96:99], v[80:81], off offset:384
	v_add_co_u32_e32 v80, vcc, 0x7800000, v180
	s_nop 1
	v_addc_co_u32_e32 v81, vcc, 0, v181, vcc
	global_load_dwordx4 v[80:83], v[80:81], off offset:384
.Lfd1_1744:
	s_waitcnt lgkmcnt(3)
	v_mfma_f32_32x32x16_bf16 v[48:63], v[152:155], v[148:151], v[48:63]
	ds_read_b128 v[140:143], v160 offset:96
	ds_read_b128 v[128:131], v160 offset:4704
	s_and_b64 vcc, exec, s[6:7]
	v_lshl_add_u64 v[182:183], v[170:171], 0, v[156:157]
	s_waitcnt lgkmcnt(4)
	v_mfma_f32_32x32x16_bf16 v[32:47], v[152:155], v[144:147], v[32:47]
	v_lshl_add_u64 v[154:155], v[172:173], 0, v[156:157]
	v_mfma_f32_32x32x16_bf16 v[16:31], v[136:139], v[148:151], v[16:31]
	ds_read_b128 v[148:151], v159 offset:36960
	ds_read_b128 v[132:135], v159 offset:41568
	s_waitcnt vmcnt(15)
	ds_write_b128 v158, v[104:107] offset:27648
	s_waitcnt vmcnt(14)
	ds_write_b128 v158, v[88:91] offset:64512
	v_mfma_f32_32x32x16_bf16 v[0:15], v[136:139], v[144:147], v[0:15]
	v_add_co_u32_e32 v88, vcc, 0x8000000, v182
	s_nop 1
	v_addc_co_u32_e32 v89, vcc, 0, v183, vcc
	global_load_dwordx4 v[104:107], v[88:89], off offset:384
	v_add_co_u32_e32 v88, vcc, 0x7800000, v154
	s_nop 1
	v_addc_co_u32_e32 v89, vcc, 0, v155, vcc
	global_load_dwordx4 v[88:91], v[88:89], off offset:384
.Lfd1_1746:
	s_waitcnt lgkmcnt(3)
	v_mfma_f32_32x32x16_bf16 v[48:63], v[140:143], v[148:151], v[48:63]
	s_and_b64 vcc, exec, s[6:7]
	v_lshl_add_u64 v[178:179], v[174:175], 0, v[156:157]
	v_lshl_add_u64 v[152:153], v[176:177], 0, v[156:157]
	s_waitcnt vmcnt(15)
	ds_write_b128 v158, v[112:115] offset:32256
	s_waitcnt vmcnt(14)
	ds_write_b128 v161, v[100:103] offset:32256
	s_waitcnt lgkmcnt(4)
	v_mfma_f32_32x32x16_bf16 v[32:47], v[140:143], v[132:135], v[32:47]
	v_mfma_f32_32x32x16_bf16 v[16:31], v[128:131], v[148:151], v[16:31]
	v_mfma_f32_32x32x16_bf16 v[0:15], v[128:131], v[132:135], v[0:15]
	v_add_co_u32_e32 v100, vcc, 0x8000000, v178
	s_nop 1
	v_addc_co_u32_e32 v101, vcc, 0, v179, vcc
	global_load_dwordx4 v[112:115], v[100:101], off offset:384
	v_add_co_u32_e32 v100, vcc, 0x7800000, v152
	s_nop 1
	v_addc_co_u32_e32 v101, vcc, 0, v153, vcc
	global_load_dwordx4 v[100:103], v[100:101], off offset:384
; #define G_LOAD(S, kt_) do { G_LD1(S##a0, S##b0, 0, kt_); G_LD1(S##a1, S##b1, 1, kt_); G_LD1(S##a2, S##b2, 2, kt_); G_LD1(S##a3, S##b3, 3, kt_); } while (0)
; #define G_STORE(S, buf_) do { G_ST1(S##a0, S##b0, 0, buf_); G_ST1(S##a1, S##b1, 1, buf_); G_ST1(S##a2, S##b2, 2, buf_); G_ST1(S##a3, S##b3, 3, buf_); } while (0)
; template <class AL, class BL>
; DI void gemm_core(AL al, BL bl, int m0, int n0, int K, char* smem, f32x16 (&acc)[2][2]) {
;     ...
;   G_LOAD(x, 0);
;   G_STORE(x, 0);
;   G_LOAD(x, 1);
;   G_LOAD(y, (nk > 2) ? 2 : 1);
;   __syncthreads();
;   for (int kt = 0; kt < nk; kt += 2) {
;     G_TILE(0, x, true, (kt + 3 < nk), kt + 3);
;     __syncthreads();
;     G_TILE(1, y, (kt + 2 < nk), (kt + 4 < nk), kt + 4);
;     __syncthreads();
;   }
.Lfd1_1748:
	s_waitcnt lgkmcnt(0)
	s_barrier
	ds_read_b128 v[132:135], v160 offset:18432
	ds_read_b128 v[144:147], v159 offset:55296
	ds_read_b128 v[140:143], v160 offset:18464
	ds_read_b128 v[136:139], v159 offset:55328
	ds_read_b128 v[148:151], v159 offset:59904
	ds_read_b128 v[128:131], v159 offset:59936
	s_waitcnt lgkmcnt(4)
	v_mfma_f32_32x32x16_bf16 v[48:63], v[132:135], v[144:147], v[48:63]
	s_cmp_lt_u32 s1, 62
	s_cselect_b64 s[8:9], -1, 0
	s_cmp_gt_u32 s1, 61
	s_cselect_b64 s[2:3], -1, 0
	s_and_b64 vcc, exec, s[2:3]
	s_waitcnt lgkmcnt(1)
	v_mfma_f32_32x32x16_bf16 v[32:47], v[132:135], v[148:151], v[32:47]
	ds_read_b128 v[190:193], v160 offset:23040
	ds_read_b128 v[132:135], v160 offset:23072
	s_waitcnt lgkmcnt(1)
	v_mfma_f32_32x32x16_bf16 v[16:31], v[190:193], v[144:147], v[16:31]
	v_mfma_f32_32x32x16_bf16 v[0:15], v[190:193], v[148:151], v[0:15]
	s_waitcnt vmcnt(15)
	ds_write_b128 v158, v[68:71]
	s_waitcnt vmcnt(14)
	ds_write_b128 v158, v[76:79] offset:36864
.Lfd1_1750:
	s_cmp_lt_u32 s1, 60
	s_cselect_b64 s[34:35], -1, 0
	s_cmp_gt_u32 s1, 59
	v_add_co_u32_e32 v68, vcc, 0x8000000, v188
	s_nop 1
	v_addc_co_u32_e32 v69, vcc, 0, v189, vcc
	v_add_co_u32_e32 v76, vcc, 0x7800000, v184
	global_load_dwordx4 v[68:71], v[68:69], off offset:512
	s_nop 0
	v_addc_co_u32_e32 v77, vcc, 0, v185, vcc
	global_load_dwordx4 v[76:79], v[76:77], off offset:512
.Lfd1_1752:
	v_mfma_f32_32x32x16_bf16 v[48:63], v[140:143], v[136:139], v[48:63]
	v_cndmask_b32_e64 v184, 0, 1, s[8:9]
	v_cmp_ne_u32_e64 s[6:7], 1, v184
	s_andn2_b64 vcc, exec, s[8:9]
	v_mfma_f32_32x32x16_bf16 v[32:47], v[140:143], v[128:131], v[32:47]
	s_waitcnt lgkmcnt(0)
	v_mfma_f32_32x32x16_bf16 v[16:31], v[132:135], v[136:139], v[16:31]
	ds_read_b128 v[144:147], v160 offset:18496
	ds_read_b128 v[136:139], v160 offset:23104
	ds_read_b128 v[148:151], v159 offset:55360
	ds_read_b128 v[140:143], v159 offset:59968
	v_mfma_f32_32x32x16_bf16 v[0:15], v[132:135], v[128:131], v[0:15]
	s_waitcnt vmcnt(15)
	ds_write_b128 v158, v[116:119] offset:4608
	s_waitcnt vmcnt(14)
	ds_write_b128 v158, v[84:87] offset:41472
.Lfd1_1754:
	v_cndmask_b32_e64 v128, 0, 1, s[34:35]
	v_cmp_ne_u32_e64 s[8:9], 1, v128
	s_andn2_b64 vcc, exec, s[34:35]
	v_add_co_u32_e32 v84, vcc, 0x8000000, v186
	s_nop 1
	v_addc_co_u32_e32 v85, vcc, 0, v187, vcc
	global_load_dwordx4 v[116:119], v[84:85], off offset:512
	v_add_co_u32_e32 v84, vcc, 0x7800000, v180
	s_nop 1
	v_addc_co_u32_e32 v85, vcc, 0, v181, vcc
	global_load_dwordx4 v[84:87], v[84:85], off offset:512
.Lfd1_1756:
	s_waitcnt lgkmcnt(1)
	v_mfma_f32_32x32x16_bf16 v[48:63], v[144:147], v[148:151], v[48:63]
	s_and_b64 vcc, exec, s[6:7]
	s_waitcnt lgkmcnt(0)
	v_mfma_f32_32x32x16_bf16 v[32:47], v[144:147], v[140:143], v[32:47]
	v_mfma_f32_32x32x16_bf16 v[16:31], v[136:139], v[148:151], v[16:31]
	ds_read_b128 v[144:147], v160 offset:18528
	ds_read_b128 v[128:131], v160 offset:23136
	ds_read_b128 v[148:151], v159 offset:55392
	ds_read_b128 v[132:135], v159 offset:60000
	v_mfma_f32_32x32x16_bf16 v[0:15], v[136:139], v[140:143], v[0:15]
	s_waitcnt vmcnt(15)
	ds_write_b128 v158, v[120:123] offset:9216
	s_waitcnt vmcnt(14)
	ds_write_b128 v158, v[92:95] offset:46080
.Lfd1_1758:
	s_and_b64 vcc, exec, s[8:9]
	v_add_co_u32_e32 v92, vcc, 0x8000000, v182
	s_nop 1
	v_addc_co_u32_e32 v93, vcc, 0, v183, vcc
	global_load_dwordx4 v[120:123], v[92:93], off offset:512
	v_add_co_u32_e32 v92, vcc, 0x7800000, v154
	s_nop 1
	v_addc_co_u32_e32 v93, vcc, 0, v155, vcc
	global_load_dwordx4 v[92:95], v[92:93], off offset:512
.Lfd1_1760:
	s_waitcnt lgkmcnt(1)
	v_mfma_f32_32x32x16_bf16 v[48:63], v[144:147], v[148:151], v[48:63]
	s_and_b64 vcc, exec, s[6:7]
	s_waitcnt lgkmcnt(0)
	v_mfma_f32_32x32x16_bf16 v[32:47], v[144:147], v[132:135], v[32:47]
	v_mfma_f32_32x32x16_bf16 v[16:31], v[128:131], v[148:151], v[16:31]
	v_mfma_f32_32x32x16_bf16 v[0:15], v[128:131], v[132:135], v[0:15]
	s_waitcnt vmcnt(15)
	ds_write_b128 v158, v[124:127] offset:13824
	s_waitcnt vmcnt(14)
	ds_write_b128 v158, v[108:111] offset:50688
.Lfd1_1762:
	s_and_b64 vcc, exec, s[8:9]
	v_add_co_u32_e32 v108, vcc, 0x8000000, v178
	s_nop 1
	v_addc_co_u32_e32 v109, vcc, 0, v179, vcc
	global_load_dwordx4 v[124:127], v[108:109], off offset:512
	v_add_co_u32_e32 v108, vcc, 0x7800000, v152
	s_nop 1
	v_addc_co_u32_e32 v109, vcc, 0, v153, vcc
	global_load_dwordx4 v[108:111], v[108:109], off offset:512
	s_branch .Lfd1_latch
